# accumulator zero-init: 64 v_mov_b64 instead of 128 v_mov_b32 before each GEMM unit; stacks on v13
# speedup vs baseline: 1.0089x; 1.0079x over previous
; template <class Epi, class Sched, bool ALIGN_EPI = false, bool SP2 = false>
; __device__ __forceinline__ void gemm_phase(PG8_LAS unsigned char* lds, const Gemm g, const Sched& S, const Epi& E) {
;     ...
;         for (int a = 0; a < 2; ++a)
; #pragma unroll
;             for (int b = 0; b < 2; ++b)
; #pragma unroll
;                 for (int m = 0; m < 4; ++m)
; #pragma unroll
;                     for (int n = 0; n < 2; ++n) acc[a][b][m][n] = (f32x4){0.f, 0.f, 0.f, 0.f};
;         cur = nxt; cA = nA; cB = nB; ++ui;
.LBB0_204:
	s_ashr_i32 s21, s20, 31
	s_lshl_b64 s[24:25], s[20:21], 20
	v_readlane_b32 s26, v236, 50
	v_readlane_b32 s27, v236, 51
	s_add_u32 s24, s26, s24
	s_addc_u32 s25, s27, s25
	s_and_b64 s[26:27], s[8:9], exec
	s_cselect_b32 s1, s25, s5
	s_cselect_b32 s3, s24, s4
	s_ashr_i32 s23, s22, 31
	s_lshl_b64 s[26:27], s[22:23], 20
	s_add_u32 s26, s10, s26
	s_addc_u32 s27, s11, s27
	s_and_b64 s[28:29], s[8:9], exec
	s_cselect_b32 s21, s27, s7
	s_cselect_b32 s23, s26, s6
	s_add_u32 s4, s4, 0x80080
	s_addc_u32 s5, s5, 0
	s_add_u32 s33, s6, 0x100
	v_mov_b64_e32 v[0:1], 0
	v_mov_b64_e32 v[2:3], 0
	v_mov_b64_e32 v[4:5], 0
	v_mov_b64_e32 v[6:7], 0
	v_mov_b64_e32 v[8:9], 0
	v_mov_b64_e32 v[10:11], 0
	v_mov_b64_e32 v[12:13], 0
	v_mov_b64_e32 v[14:15], 0
	v_mov_b64_e32 v[16:17], 0
	v_mov_b64_e32 v[18:19], 0
	v_mov_b64_e32 v[20:21], 0
	v_mov_b64_e32 v[22:23], 0
	v_mov_b64_e32 v[24:25], 0
	v_mov_b64_e32 v[26:27], 0
	v_mov_b64_e32 v[28:29], 0
	v_mov_b64_e32 v[30:31], 0
	v_mov_b64_e32 v[32:33], 0
	v_mov_b64_e32 v[34:35], 0
	v_mov_b64_e32 v[36:37], 0
	v_mov_b64_e32 v[38:39], 0
	v_mov_b64_e32 v[40:41], 0
	v_mov_b64_e32 v[42:43], 0
	v_mov_b64_e32 v[44:45], 0
	v_mov_b64_e32 v[46:47], 0
	v_mov_b64_e32 v[48:49], 0
	v_mov_b64_e32 v[50:51], 0
	v_mov_b64_e32 v[52:53], 0
	v_mov_b64_e32 v[54:55], 0
	v_mov_b64_e32 v[56:57], 0
	v_mov_b64_e32 v[58:59], 0
	v_mov_b64_e32 v[60:61], 0
	v_mov_b64_e32 v[62:63], 0
	v_mov_b64_e32 v[64:65], 0
	v_mov_b64_e32 v[66:67], 0
	v_mov_b64_e32 v[68:69], 0
	v_mov_b64_e32 v[70:71], 0
	v_mov_b64_e32 v[72:73], 0
	v_mov_b64_e32 v[74:75], 0
	v_mov_b64_e32 v[76:77], 0
	v_mov_b64_e32 v[78:79], 0
	v_mov_b64_e32 v[80:81], 0
	v_mov_b64_e32 v[82:83], 0
	v_mov_b64_e32 v[84:85], 0
	v_mov_b64_e32 v[86:87], 0
	v_mov_b64_e32 v[88:89], 0
	v_mov_b64_e32 v[90:91], 0
	v_mov_b64_e32 v[92:93], 0
	v_mov_b64_e32 v[94:95], 0
	v_mov_b64_e32 v[96:97], 0
	v_mov_b64_e32 v[98:99], 0
	v_mov_b64_e32 v[100:101], 0
	v_mov_b64_e32 v[102:103], 0
	v_mov_b64_e32 v[104:105], 0
	v_mov_b64_e32 v[106:107], 0
	v_mov_b64_e32 v[108:109], 0
	v_mov_b64_e32 v[110:111], 0
	v_mov_b64_e32 v[112:113], 0
	v_mov_b64_e32 v[114:115], 0
	v_mov_b64_e32 v[116:117], 0
	v_mov_b64_e32 v[118:119], 0
	v_mov_b64_e32 v[120:121], 0
	v_mov_b64_e32 v[122:123], 0
	v_mov_b64_e32 v[124:125], 0
	v_mov_b64_e32 v[126:127], 0
	s_addc_u32 s50, s7, 0
	s_mov_b32 s51, -2
	s_waitcnt vmcnt(0)

; template <class Epi, class Sched, bool ALIGN_EPI = false, bool SP2 = false>
; __device__ __forceinline__ void gemm_phase(PG8_LAS unsigned char* lds, const Gemm g, const Sched& S, const Epi& E) {
;     ...
;         for (int a = 0; a < 2; ++a)
; #pragma unroll
;             for (int b = 0; b < 2; ++b)
; #pragma unroll
;                 for (int m = 0; m < 4; ++m)
; #pragma unroll
;                     for (int n = 0; n < 2; ++n) acc[a][b][m][n] = (f32x4){0.f, 0.f, 0.f, 0.f};
;         cur = nxt; cA = nA; cB = nB; ++ui;
.LBB0_571:
	s_bitcmp0_b32 s7, 0
	s_cselect_b64 s[16:17], -1, 0
	s_and_b64 s[16:17], s[16:17], s[4:5]
	s_add_i32 s7, s14, 64
	s_add_i32 s13, s12, 8
	s_and_b64 s[16:17], s[16:17], exec
	s_cselect_b32 s14, s7, s14
	s_cselect_b32 s12, s13, s12
	s_ashr_i32 s15, s14, 31
	s_lshl_b64 s[16:17], s[14:15], 19
	s_add_u32 s16, s29, s16
	s_addc_u32 s17, s30, s17
	s_and_b64 s[18:19], s[4:5], exec
	s_cselect_b32 s7, s17, s23
	s_cselect_b32 s15, s16, s22
	s_ashr_i32 s13, s12, 31
	s_lshl_b64 s[18:19], s[12:13], 19
	v_readlane_b32 s26, v236, 41
	v_readlane_b32 s27, v236, 42
	s_add_u32 s18, s26, s18
	s_addc_u32 s19, s27, s19
	s_and_b64 s[26:27], s[4:5], exec
	s_cselect_b32 s13, s19, s25
	s_cselect_b32 s21, s18, s24
	s_add_u32 s22, s22, 0x40080
	s_addc_u32 s23, s23, 0
	s_add_u32 s44, s24, 0x100
	v_mov_b64_e32 v[0:1], 0
	v_mov_b64_e32 v[2:3], 0
	v_mov_b64_e32 v[4:5], 0
	v_mov_b64_e32 v[6:7], 0
	v_mov_b64_e32 v[8:9], 0
	v_mov_b64_e32 v[10:11], 0
	v_mov_b64_e32 v[12:13], 0
	v_mov_b64_e32 v[14:15], 0
	v_mov_b64_e32 v[16:17], 0
	v_mov_b64_e32 v[18:19], 0
	v_mov_b64_e32 v[20:21], 0
	v_mov_b64_e32 v[22:23], 0
	v_mov_b64_e32 v[24:25], 0
	v_mov_b64_e32 v[26:27], 0
	v_mov_b64_e32 v[28:29], 0
	v_mov_b64_e32 v[30:31], 0
	v_mov_b64_e32 v[32:33], 0
	v_mov_b64_e32 v[34:35], 0
	v_mov_b64_e32 v[36:37], 0
	v_mov_b64_e32 v[38:39], 0
	v_mov_b64_e32 v[40:41], 0
	v_mov_b64_e32 v[42:43], 0
	v_mov_b64_e32 v[44:45], 0
	v_mov_b64_e32 v[46:47], 0
	v_mov_b64_e32 v[48:49], 0
	v_mov_b64_e32 v[50:51], 0
	v_mov_b64_e32 v[52:53], 0
	v_mov_b64_e32 v[54:55], 0
	v_mov_b64_e32 v[56:57], 0
	v_mov_b64_e32 v[58:59], 0
	v_mov_b64_e32 v[60:61], 0
	v_mov_b64_e32 v[62:63], 0
	v_mov_b64_e32 v[64:65], 0
	v_mov_b64_e32 v[66:67], 0
	v_mov_b64_e32 v[68:69], 0
	v_mov_b64_e32 v[70:71], 0
	v_mov_b64_e32 v[72:73], 0
	v_mov_b64_e32 v[74:75], 0
	v_mov_b64_e32 v[76:77], 0
	v_mov_b64_e32 v[78:79], 0
	v_mov_b64_e32 v[80:81], 0
	v_mov_b64_e32 v[82:83], 0
	v_mov_b64_e32 v[84:85], 0
	v_mov_b64_e32 v[86:87], 0
	v_mov_b64_e32 v[88:89], 0
	v_mov_b64_e32 v[90:91], 0
	v_mov_b64_e32 v[92:93], 0
	v_mov_b64_e32 v[94:95], 0
	v_mov_b64_e32 v[96:97], 0
	v_mov_b64_e32 v[98:99], 0
	v_mov_b64_e32 v[100:101], 0
	v_mov_b64_e32 v[102:103], 0
	v_mov_b64_e32 v[104:105], 0
	v_mov_b64_e32 v[106:107], 0
	v_mov_b64_e32 v[108:109], 0
	v_mov_b64_e32 v[110:111], 0
	v_mov_b64_e32 v[112:113], 0
	v_mov_b64_e32 v[114:115], 0
	v_mov_b64_e32 v[116:117], 0
	v_mov_b64_e32 v[118:119], 0
	v_mov_b64_e32 v[120:121], 0
	v_mov_b64_e32 v[122:123], 0
	v_mov_b64_e32 v[124:125], 0
	v_mov_b64_e32 v[126:127], 0
	s_addc_u32 s45, s25, 0
	s_mov_b32 s46, -2

; template <class Epi, class Sched, bool ALIGN_EPI = false, bool SP2 = false>
; __device__ __forceinline__ void gemm_phase(PG8_LAS unsigned char* lds, const Gemm g, const Sched& S, const Epi& E) {
;     ...
;         for (int a = 0; a < 2; ++a)
; #pragma unroll
;             for (int b = 0; b < 2; ++b)
; #pragma unroll
;                 for (int m = 0; m < 4; ++m)
; #pragma unroll
;                     for (int n = 0; n < 2; ++n) acc[a][b][m][n] = (f32x4){0.f, 0.f, 0.f, 0.f};
;         cur = nxt; cA = nA; cB = nB; ++ui;
.LBB0_893:
	s_ashr_i32 s25, s24, 31
	s_lshl_b64 s[28:29], s[24:25], 20
	v_readlane_b32 s30, v236, 50
	v_readlane_b32 s31, v236, 51
	s_add_u32 s28, s30, s28
	s_addc_u32 s29, s31, s29
	s_and_b64 s[30:31], s[6:7], exec
	s_cselect_b32 s25, s29, s39
	s_cselect_b32 s35, s28, s38
	s_ashr_i32 s27, s26, 31
	s_lshl_b64 s[30:31], s[26:27], 20
	v_readlane_b32 s42, v236, 43
	v_readlane_b32 s43, v236, 44
	s_add_u32 s30, s42, s30
	s_addc_u32 s31, s43, s31
	s_and_b64 s[42:43], s[6:7], exec
	s_cselect_b32 s27, s31, s41
	s_cselect_b32 s55, s30, s40
	s_add_u32 s38, s38, 0x80080
	s_addc_u32 s39, s39, 0
	s_add_u32 s56, s40, 0x100
	v_mov_b64_e32 v[0:1], 0
	v_mov_b64_e32 v[2:3], 0
	v_mov_b64_e32 v[4:5], 0
	v_mov_b64_e32 v[6:7], 0
	v_mov_b64_e32 v[8:9], 0
	v_mov_b64_e32 v[10:11], 0
	v_mov_b64_e32 v[12:13], 0
	v_mov_b64_e32 v[14:15], 0
	v_mov_b64_e32 v[16:17], 0
	v_mov_b64_e32 v[18:19], 0
	v_mov_b64_e32 v[20:21], 0
	v_mov_b64_e32 v[22:23], 0
	v_mov_b64_e32 v[24:25], 0
	v_mov_b64_e32 v[26:27], 0
	v_mov_b64_e32 v[28:29], 0
	v_mov_b64_e32 v[30:31], 0
	v_mov_b64_e32 v[32:33], 0
	v_mov_b64_e32 v[34:35], 0
	v_mov_b64_e32 v[36:37], 0
	v_mov_b64_e32 v[38:39], 0
	v_mov_b64_e32 v[40:41], 0
	v_mov_b64_e32 v[42:43], 0
	v_mov_b64_e32 v[44:45], 0
	v_mov_b64_e32 v[46:47], 0
	v_mov_b64_e32 v[48:49], 0
	v_mov_b64_e32 v[50:51], 0
	v_mov_b64_e32 v[52:53], 0
	v_mov_b64_e32 v[54:55], 0
	v_mov_b64_e32 v[56:57], 0
	v_mov_b64_e32 v[58:59], 0
	v_mov_b64_e32 v[60:61], 0
	v_mov_b64_e32 v[62:63], 0
	v_mov_b64_e32 v[64:65], 0
	v_mov_b64_e32 v[66:67], 0
	v_mov_b64_e32 v[68:69], 0
	v_mov_b64_e32 v[70:71], 0
	v_mov_b64_e32 v[76:77], 0
	v_mov_b64_e32 v[78:79], 0
	v_mov_b64_e32 v[80:81], 0
	v_mov_b64_e32 v[82:83], 0
	v_mov_b64_e32 v[88:89], 0
	v_mov_b64_e32 v[90:91], 0
	v_mov_b64_e32 v[100:101], 0
	v_mov_b64_e32 v[102:103], 0
	v_mov_b64_e32 v[104:105], 0
	v_mov_b64_e32 v[106:107], 0
	v_mov_b64_e32 v[108:109], 0
	v_mov_b64_e32 v[110:111], 0
	v_mov_b64_e32 v[112:113], 0
	v_mov_b64_e32 v[114:115], 0
	v_mov_b64_e32 v[116:117], 0
	v_mov_b64_e32 v[118:119], 0
	v_mov_b64_e32 v[120:121], 0
	v_mov_b64_e32 v[122:123], 0
	v_mov_b64_e32 v[124:125], 0
	v_mov_b64_e32 v[126:127], 0
	v_mov_b64_e32 v[128:129], 0
	v_mov_b64_e32 v[130:131], 0
	v_mov_b64_e32 v[132:133], 0
	v_mov_b64_e32 v[134:135], 0
	v_mov_b64_e32 v[136:137], 0
	v_mov_b64_e32 v[138:139], 0
	v_mov_b64_e32 v[140:141], 0
	v_mov_b64_e32 v[142:143], 0
	s_addc_u32 s57, s41, 0
	s_mov_b32 s58, -2
	s_waitcnt lgkmcnt(0)

; template <class Epi, class Sched, bool ALIGN_EPI = false, bool SP2 = false>
; __device__ __forceinline__ void gemm_phase(PG8_LAS unsigned char* lds, const Gemm g, const Sched& S, const Epi& E) {
;     ...
;         for (int a = 0; a < 2; ++a)
; #pragma unroll
;             for (int b = 0; b < 2; ++b)
; #pragma unroll
;                 for (int m = 0; m < 4; ++m)
; #pragma unroll
;                     for (int n = 0; n < 2; ++n) acc[a][b][m][n] = (f32x4){0.f, 0.f, 0.f, 0.f};
;         cur = nxt; cA = nA; cB = nB; ++ui;
.LBB0_993:
	s_ashr_i32 s15, s14, 31
	s_lshl_b64 s[18:19], s[14:15], 20
	s_add_u32 s18, s8, s18
	s_addc_u32 s19, s9, s19
	s_and_b64 s[20:21], s[4:5], exec
	s_cselect_b32 s15, s19, s25
	s_cselect_b32 s43, s18, s24
	s_ashr_i32 s17, s16, 31
	s_lshl_b64 s[20:21], s[16:17], 20
	v_readlane_b32 s28, v236, 52
	v_readlane_b32 s29, v236, 53
	s_add_u32 s20, s28, s20
	s_addc_u32 s21, s29, s21
	s_and_b64 s[28:29], s[4:5], exec
	s_cselect_b32 s17, s21, s27
	s_cselect_b32 s44, s20, s26
	s_add_u32 s24, s24, 0x80080
	s_addc_u32 s25, s25, 0
	s_add_u32 s45, s26, 0x100
	v_mov_b64_e32 v[0:1], 0
	v_mov_b64_e32 v[2:3], 0
	v_mov_b64_e32 v[4:5], 0
	v_mov_b64_e32 v[6:7], 0
	v_mov_b64_e32 v[8:9], 0
	v_mov_b64_e32 v[10:11], 0
	v_mov_b64_e32 v[12:13], 0
	v_mov_b64_e32 v[14:15], 0
	v_mov_b64_e32 v[16:17], 0
	v_mov_b64_e32 v[18:19], 0
	v_mov_b64_e32 v[20:21], 0
	v_mov_b64_e32 v[22:23], 0
	v_mov_b64_e32 v[24:25], 0
	v_mov_b64_e32 v[26:27], 0
	v_mov_b64_e32 v[28:29], 0
	v_mov_b64_e32 v[30:31], 0
	v_mov_b64_e32 v[32:33], 0
	v_mov_b64_e32 v[34:35], 0
	v_mov_b64_e32 v[36:37], 0
	v_mov_b64_e32 v[38:39], 0
	v_mov_b64_e32 v[40:41], 0
	v_mov_b64_e32 v[42:43], 0
	v_mov_b64_e32 v[44:45], 0
	v_mov_b64_e32 v[46:47], 0
	v_mov_b64_e32 v[48:49], 0
	v_mov_b64_e32 v[50:51], 0
	v_mov_b64_e32 v[52:53], 0
	v_mov_b64_e32 v[54:55], 0
	v_mov_b64_e32 v[56:57], 0
	v_mov_b64_e32 v[58:59], 0
	v_mov_b64_e32 v[60:61], 0
	v_mov_b64_e32 v[62:63], 0
	v_mov_b64_e32 v[64:65], 0
	v_mov_b64_e32 v[66:67], 0
	v_mov_b64_e32 v[68:69], 0
	v_mov_b64_e32 v[70:71], 0
	v_mov_b64_e32 v[72:73], 0
	v_mov_b64_e32 v[74:75], 0
	v_mov_b64_e32 v[76:77], 0
	v_mov_b64_e32 v[78:79], 0
	v_mov_b64_e32 v[80:81], 0
	v_mov_b64_e32 v[82:83], 0
	v_mov_b64_e32 v[84:85], 0
	v_mov_b64_e32 v[86:87], 0
	v_mov_b64_e32 v[88:89], 0
	v_mov_b64_e32 v[90:91], 0
	v_mov_b64_e32 v[92:93], 0
	v_mov_b64_e32 v[94:95], 0
	v_mov_b64_e32 v[96:97], 0
	v_mov_b64_e32 v[98:99], 0
	v_mov_b64_e32 v[100:101], 0
	v_mov_b64_e32 v[102:103], 0
	v_mov_b64_e32 v[104:105], 0
	v_mov_b64_e32 v[106:107], 0
	v_mov_b64_e32 v[108:109], 0
	v_mov_b64_e32 v[110:111], 0
	v_mov_b64_e32 v[112:113], 0
	v_mov_b64_e32 v[114:115], 0
	v_mov_b64_e32 v[116:117], 0
	v_mov_b64_e32 v[118:119], 0
	v_mov_b64_e32 v[120:121], 0
	v_mov_b64_e32 v[122:123], 0
	v_mov_b64_e32 v[124:125], 0
	v_mov_b64_e32 v[126:127], 0
	s_addc_u32 s46, s27, 0
	s_mov_b32 s47, -2

; template <class Epi, class Sched, bool ALIGN_EPI = false, bool SP2 = false>
; __device__ __forceinline__ void gemm_phase(PG8_LAS unsigned char* lds, const Gemm g, const Sched& S, const Epi& E) {
;     ...
;         for (int a = 0; a < 2; ++a)
; #pragma unroll
;             for (int b = 0; b < 2; ++b)
; #pragma unroll
;                 for (int m = 0; m < 4; ++m)
; #pragma unroll
;                     for (int n = 0; n < 2; ++n) acc[a][b][m][n] = (f32x4){0.f, 0.f, 0.f, 0.f};
;         cur = nxt; cA = nA; cB = nB; ++ui;
.LBB0_1070:
	s_ashr_i32 s19, s18, 31
	s_lshl_b64 s[20:21], s[18:19], 22
	s_add_u32 s20, s72, s20
	s_addc_u32 s21, s73, s21
	s_and_b64 s[22:23], s[0:1], exec
	s_cselect_b32 s19, s21, s27
	s_cselect_b32 s51, s20, s26
	s_ashr_i32 s17, s16, 31
	s_lshl_b64 s[22:23], s[16:17], 22
	v_readlane_b32 s30, v236, 54
	v_readlane_b32 s31, v236, 55
	s_add_u32 s22, s30, s22
	s_addc_u32 s23, s31, s23
	s_and_b64 s[30:31], s[0:1], exec
	s_cselect_b32 s17, s23, s29
	s_cselect_b32 s52, s22, s28
	s_add_u32 s26, s26, 0x200080
	s_addc_u32 s27, s27, 0
	s_add_u32 s53, s28, 0x100
	v_mov_b64_e32 v[0:1], 0
	v_mov_b64_e32 v[2:3], 0
	v_mov_b64_e32 v[4:5], 0
	v_mov_b64_e32 v[6:7], 0
	v_mov_b64_e32 v[8:9], 0
	v_mov_b64_e32 v[10:11], 0
	v_mov_b64_e32 v[12:13], 0
	v_mov_b64_e32 v[14:15], 0
	v_mov_b64_e32 v[16:17], 0
	v_mov_b64_e32 v[18:19], 0
	v_mov_b64_e32 v[20:21], 0
	v_mov_b64_e32 v[22:23], 0
	v_mov_b64_e32 v[24:25], 0
	v_mov_b64_e32 v[26:27], 0
	v_mov_b64_e32 v[28:29], 0
	v_mov_b64_e32 v[30:31], 0
	v_mov_b64_e32 v[32:33], 0
	v_mov_b64_e32 v[34:35], 0
	v_mov_b64_e32 v[36:37], 0
	v_mov_b64_e32 v[38:39], 0
	v_mov_b64_e32 v[40:41], 0
	v_mov_b64_e32 v[42:43], 0
	v_mov_b64_e32 v[44:45], 0
	v_mov_b64_e32 v[46:47], 0
	v_mov_b64_e32 v[48:49], 0
	v_mov_b64_e32 v[50:51], 0
	v_mov_b64_e32 v[52:53], 0
	v_mov_b64_e32 v[54:55], 0
	v_mov_b64_e32 v[56:57], 0
	v_mov_b64_e32 v[58:59], 0
	v_mov_b64_e32 v[60:61], 0
	v_mov_b64_e32 v[62:63], 0
	v_mov_b64_e32 v[68:69], 0
	v_mov_b64_e32 v[70:71], 0
	v_mov_b64_e32 v[72:73], 0
	v_mov_b64_e32 v[74:75], 0
	v_mov_b64_e32 v[76:77], 0
	v_mov_b64_e32 v[78:79], 0
	v_mov_b64_e32 v[80:81], 0
	v_mov_b64_e32 v[82:83], 0
	v_mov_b64_e32 v[84:85], 0
	v_mov_b64_e32 v[86:87], 0
	v_mov_b64_e32 v[88:89], 0
	v_mov_b64_e32 v[90:91], 0
	v_mov_b64_e32 v[92:93], 0
	v_mov_b64_e32 v[94:95], 0
	v_mov_b64_e32 v[96:97], 0
	v_mov_b64_e32 v[98:99], 0
	v_mov_b64_e32 v[100:101], 0
	v_mov_b64_e32 v[102:103], 0
	v_mov_b64_e32 v[104:105], 0
	v_mov_b64_e32 v[106:107], 0
	v_mov_b64_e32 v[112:113], 0
	v_mov_b64_e32 v[114:115], 0
	v_mov_b64_e32 v[120:121], 0
	v_mov_b64_e32 v[122:123], 0
	v_mov_b64_e32 v[124:125], 0
	v_mov_b64_e32 v[126:127], 0
	v_mov_b64_e32 v[132:133], 0
	v_mov_b64_e32 v[134:135], 0
	v_mov_b64_e32 v[136:137], 0
	v_mov_b64_e32 v[138:139], 0
	v_mov_b64_e32 v[140:141], 0
	v_mov_b64_e32 v[142:143], 0
	s_addc_u32 s54, s29, 0
	s_mov_b32 s55, -2
